# v70 + barrier census loads batched + norm1 context-row split-K partial sum: 20 loads issued up front instead of 16 serialized round trips
# speedup vs baseline: 1.0075x; 1.0037x over previous
.LBB0_15:
	v_readlane_b32 s2, v251, 9
	v_readlane_b32 s3, v251, 10
	s_mov_b64 s[22:23], -1
	s_nop 3
	global_load_dword v0, v1, s[2:3] sc1
	v_readlane_b32 s2, v251, 11
	v_readlane_b32 s3, v251, 12
	s_nop 4
	global_load_dword v2, v1, s[2:3] sc1
	v_readlane_b32 s2, v251, 13
	v_readlane_b32 s3, v251, 14
	s_nop 1
	s_nop 2
	global_load_dword v3, v1, s[2:3] sc1
	v_readlane_b32 s2, v251, 15
	v_readlane_b32 s3, v251, 16
	s_nop 1
	s_nop 2
	global_load_dword v4, v1, s[2:3] sc1
	v_readlane_b32 s2, v251, 17
	v_readlane_b32 s3, v251, 18
	s_nop 1
	s_nop 2
	global_load_dword v5, v1, s[2:3] sc1
	v_readlane_b32 s2, v251, 19
	v_readlane_b32 s3, v251, 20
	s_nop 1
	s_nop 2
	global_load_dword v6, v1, s[2:3] sc1
	v_readlane_b32 s2, v251, 21
	v_readlane_b32 s3, v251, 22
	s_nop 1
	s_nop 2
	global_load_dword v7, v1, s[2:3] sc1
	v_readlane_b32 s2, v251, 23
	v_readlane_b32 s3, v251, 24
	s_nop 1
	s_nop 2
	global_load_dword v8, v1, s[2:3] sc1
	v_readlane_b32 s2, v251, 25
	v_readlane_b32 s3, v251, 26
	s_nop 1
	s_nop 2
	global_load_dword v9, v1, s[2:3] sc1
	v_readlane_b32 s2, v251, 27
	v_readlane_b32 s3, v251, 28
	s_nop 1
	s_nop 2
	global_load_dword v10, v1, s[2:3] sc1
	v_readlane_b32 s2, v251, 29
	v_readlane_b32 s3, v251, 30
	s_nop 1
	s_nop 2
	global_load_dword v11, v1, s[2:3] sc1
	v_readlane_b32 s2, v251, 31
	v_readlane_b32 s3, v251, 32
	s_nop 1
	s_nop 2
	global_load_dword v12, v1, s[2:3] sc1
	v_readlane_b32 s2, v251, 33
	v_readlane_b32 s3, v251, 34
	s_nop 1
	s_nop 2
	global_load_dword v13, v1, s[2:3] sc1
	v_readlane_b32 s2, v251, 35
	v_readlane_b32 s3, v251, 36
	s_nop 1
	s_nop 2
	global_load_dword v14, v1, s[2:3] sc1
	v_readlane_b32 s2, v251, 37
	v_readlane_b32 s3, v251, 38
	s_nop 1
	s_nop 2
	global_load_dword v15, v1, s[2:3] sc1
	v_readlane_b32 s2, v251, 39
	v_readlane_b32 s3, v251, 40
	s_nop 1
	s_nop 2
	global_load_dword v16, v1, s[2:3] sc1
	s_mov_b64 s[2:3], -1
	s_waitcnt vmcnt(0)
	v_add_u32_e32 v17, v2, v0
	v_add_u32_e32 v17, v17, v3
	v_add_u32_e32 v17, v17, v4
	v_add_u32_e32 v17, v17, v5
	v_add_u32_e32 v17, v17, v6
	v_add_u32_e32 v17, v17, v7
	v_add_u32_e32 v17, v17, v8
	v_add_u32_e32 v17, v17, v9
	v_add_u32_e32 v17, v17, v10
	v_add_u32_e32 v17, v17, v11
	v_add_u32_e32 v17, v17, v12
	v_add_u32_e32 v17, v17, v13
	v_add_u32_e32 v17, v17, v14
	v_add_u32_e32 v17, v17, v15
	v_add_u32_e32 v17, v17, v16
	v_cmp_eq_u32_e32 vcc, s4, v17
	s_cbranch_vccnz .LBB0_14
	s_and_b32 s2, s5, 0xff
	s_cmp_eq_u32 s2, 0
	s_mov_b64 s[2:3], -1
	s_mov_b64 s[24:25], -1
	s_sleep 1
	s_cbranch_scc1 .LBB0_19
	s_and_b64 vcc, exec, s[24:25]
	s_cbranch_vccz .LBB0_14

.LBB0_443:
	v_readlane_b32 s56, v254, 4
	v_min_i32_e32 v6, s6, v66
	v_readlane_b32 s71, v254, 19
	v_add_u32_e32 v0, 0xffff8000, v6
	v_ashrrev_i32_e32 v2, 31, v6
	v_cmp_gt_i32_e32 vcc, s40, v6
	v_mov_b32_e32 v4, s55
	v_readlane_b32 s70, v254, 18
	v_mov_b32_e32 v5, s71
	v_cndmask_b32_e32 v3, 0, v2, vcc
	v_cndmask_b32_e32 v2, v0, v6, vcc
	v_cndmask_b32_e32 v5, v4, v5, vcc
	v_mov_b32_e32 v4, s54
	v_mov_b32_e32 v7, s70
	v_cndmask_b32_e32 v4, v4, v7, vcc
	v_lshlrev_b64 v[2:3], 12, v[2:3]
	v_lshl_add_u64 v[2:3], v[4:5], 0, v[2:3]
	v_mov_b32_e32 v85, v1
	v_lshl_add_u64 v[2:3], v[2:3], 0, v[84:85]
	global_load_dwordx4 v[62:65], v[2:3], off nt
	global_load_dwordx4 v[50:53], v[2:3], off offset:1024 nt
	global_load_dwordx4 v[46:49], v[2:3], off offset:2048 nt
	global_load_dwordx4 v[30:33], v[2:3], off offset:3072 nt
	v_cmp_lt_i32_e32 vcc, s14, v6
	v_readlane_b32 s57, v254, 5
	v_readlane_b32 s58, v254, 6
	v_readlane_b32 s59, v254, 7
	v_readlane_b32 s60, v254, 8
	v_readlane_b32 s61, v254, 9
	v_readlane_b32 s62, v254, 10
	v_readlane_b32 s63, v254, 11
	v_readlane_b32 s64, v254, 12
	v_readlane_b32 s65, v254, 13
	v_readlane_b32 s66, v254, 14
	v_readlane_b32 s67, v254, 15
	v_readlane_b32 s68, v254, 16
	v_readlane_b32 s69, v254, 17
	s_and_saveexec_b64 s[36:37], vcc
	s_cbranch_execz .LBB0_445
	v_readlane_b32 s10, v253, 18
	v_lshlrev_b64 v[2:3], 12, v[0:1]
	v_readlane_b32 s11, v253, 19
	v_mov_b32_e32 v87, v1
	v_mov_b32_e32 v89, v1
	v_lshl_add_u64 v[10:11], s[10:11], 0, v[2:3]
	s_mov_b64 s[10:11], 0x800000
	v_lshl_add_u64 v[8:9], v[10:11], 0, s[10:11]
	s_mov_b64 s[10:11], 0x1000000
	v_lshl_add_u64 v[6:7], v[10:11], 0, s[10:11]
	s_mov_b64 s[10:11], 0x1800000
	v_lshl_add_u64 v[4:5], v[10:11], 0, s[10:11]
	v_lshl_add_u64 v[10:11], v[10:11], 0, v[84:85]
	v_lshl_add_u64 v[8:9], v[8:9], 0, v[84:85]
	v_lshl_add_u64 v[6:7], v[6:7], 0, v[84:85]
	v_lshl_add_u64 v[4:5], v[4:5], 0, v[84:85]
	v_mov_b32_e32 v91, v1
	v_lshl_add_u64 v[2:3], v[78:79], 0, v[2:3]
	global_load_dwordx4 v[114:117], v[10:11], off
	global_load_dwordx4 v[118:121], v[8:9], off
	global_load_dwordx4 v[122:125], v[6:7], off
	global_load_dwordx4 v[126:129], v[4:5], off
	global_load_dwordx4 v[200:203], v[68:69], off
	global_load_dwordx4 v[130:133], v[10:11], off offset:1024
	global_load_dwordx4 v[134:137], v[8:9], off offset:1024
	global_load_dwordx4 v[138:141], v[6:7], off offset:1024
	global_load_dwordx4 v[142:145], v[4:5], off offset:1024
	global_load_dwordx4 v[204:207], v[70:71], off
	global_load_dwordx4 v[146:149], v[10:11], off offset:2048
	global_load_dwordx4 v[150:153], v[8:9], off offset:2048
	global_load_dwordx4 v[176:179], v[6:7], off offset:2048
	global_load_dwordx4 v[180:183], v[4:5], off offset:2048
	global_load_dwordx4 v[208:211], v[72:73], off
	global_load_dwordx4 v[184:187], v[10:11], off offset:3072
	global_load_dwordx4 v[188:191], v[8:9], off offset:3072
	global_load_dwordx4 v[192:195], v[6:7], off offset:3072
	global_load_dwordx4 v[196:199], v[4:5], off offset:3072
	global_load_dwordx4 v[20:23], v[74:75], off
	s_waitcnt vmcnt(15)
	v_pk_add_f32 v[114:115], v[114:115], v[118:119]
	v_pk_add_f32 v[116:117], v[116:117], v[120:121]
	v_pk_add_f32 v[114:115], v[114:115], v[122:123]
	v_pk_add_f32 v[116:117], v[116:117], v[124:125]
	v_pk_add_f32 v[114:115], v[114:115], v[126:127]
	v_pk_add_f32 v[116:117], v[116:117], v[128:129]
	v_pk_fma_f32 v[62:63], v[114:115], v[200:201], v[62:63]
	v_pk_fma_f32 v[64:65], v[116:117], v[202:203], v[64:65]
	global_store_dwordx4 v[2:3], v[62:65], off
	s_waitcnt vmcnt(11)
	v_pk_add_f32 v[130:131], v[130:131], v[134:135]
	v_pk_add_f32 v[132:133], v[132:133], v[136:137]
	v_pk_add_f32 v[130:131], v[130:131], v[138:139]
	v_pk_add_f32 v[132:133], v[132:133], v[140:141]
	v_pk_add_f32 v[130:131], v[130:131], v[142:143]
	v_pk_add_f32 v[132:133], v[132:133], v[144:145]
	v_pk_fma_f32 v[50:51], v[130:131], v[204:205], v[50:51]
	v_pk_fma_f32 v[52:53], v[132:133], v[206:207], v[52:53]
	global_store_dwordx4 v[2:3], v[50:53], off offset:1024
	s_waitcnt vmcnt(7)
	v_pk_add_f32 v[146:147], v[146:147], v[150:151]
	v_pk_add_f32 v[148:149], v[148:149], v[152:153]
	v_pk_add_f32 v[146:147], v[146:147], v[176:177]
	v_pk_add_f32 v[148:149], v[148:149], v[178:179]
	v_pk_add_f32 v[146:147], v[146:147], v[180:181]
	v_pk_add_f32 v[148:149], v[148:149], v[182:183]
	v_pk_fma_f32 v[46:47], v[146:147], v[208:209], v[46:47]
	v_pk_fma_f32 v[48:49], v[148:149], v[210:211], v[48:49]
	global_store_dwordx4 v[2:3], v[46:49], off offset:2048
	s_waitcnt vmcnt(3)
	v_pk_add_f32 v[184:185], v[184:185], v[188:189]
	v_pk_add_f32 v[186:187], v[186:187], v[190:191]
	v_pk_add_f32 v[184:185], v[184:185], v[192:193]
	v_pk_add_f32 v[186:187], v[186:187], v[194:195]
	v_pk_add_f32 v[184:185], v[184:185], v[196:197]
	v_pk_add_f32 v[186:187], v[186:187], v[198:199]
	v_pk_fma_f32 v[30:31], v[184:185], v[20:21], v[30:31]
	v_pk_fma_f32 v[32:33], v[186:187], v[22:23], v[32:33]
	global_store_dwordx4 v[2:3], v[30:33], off offset:3072

.LBB0_480:
	v_mul_f32_e32 v0, v23, v23
	v_mul_f32_e32 v14, v11, v11
	v_fmac_f32_e32 v0, v22, v22
	v_fmac_f32_e32 v14, v10, v10
	v_fmac_f32_e32 v0, v24, v24
	v_fmac_f32_e32 v14, v12, v12
	v_fmac_f32_e32 v0, v25, v25
	v_fmac_f32_e32 v14, v13, v13
	v_add_f32_e32 v0, v14, v0
	v_mul_f32_e32 v14, v7, v7
	v_fmac_f32_e32 v14, v6, v6
	v_fmac_f32_e32 v14, v8, v8
	v_fmac_f32_e32 v14, v9, v9
	v_add_f32_e32 v0, v14, v0
	v_mul_f32_e32 v14, v3, v3
	v_fmac_f32_e32 v14, v2, v2
	v_fmac_f32_e32 v14, v4, v4
	v_fmac_f32_e32 v14, v5, v5
	v_add_f32_e32 v0, v14, v0
	v_min_i32_e32 v14, 0x8000, v92
	v_ashrrev_i32_e32 v14, 12, v14
	v_mul_i32_i24_e32 v14, 0x1800, v14
	v_ashrrev_i32_e32 v15, 31, v14
	v_lshl_add_u64 v[20:21], v[14:15], 2, s[22:23]
	ds_bpermute_b32 v14, v108, v0
	v_lshl_add_u64 v[18:19], v[20:21], 0, s[10:11]
	v_mov_b32_e32 v85, v1
	v_lshl_add_u64 v[26:27], v[18:19], 0, v[84:85]
	global_load_dwordx4 v[28:31], v[26:27], off
	s_waitcnt lgkmcnt(0)
	v_add_f32_e32 v0, v0, v14
	ds_bpermute_b32 v14, v109, v0
	v_lshl_add_u64 v[26:27], v[20:21], 0, v[84:85]
	global_load_dwordx4 v[32:35], v[26:27], off
	v_ashrrev_i32_e32 v93, 31, v92
	v_lshlrev_b64 v[36:37], 11, v[92:93]
	s_waitcnt lgkmcnt(0)
	v_add_f32_e32 v0, v0, v14
	ds_bpermute_b32 v14, v110, v0
	v_mov_b32_e32 v87, v1
	v_mov_b32_e32 v89, v1
	v_mov_b32_e32 v91, v1
	s_waitcnt lgkmcnt(0)
	v_add_f32_e32 v0, v0, v14
	ds_bpermute_b32 v14, v111, v0
	s_waitcnt lgkmcnt(0)
	v_add_f32_e32 v0, v0, v14
	ds_bpermute_b32 v14, v112, v0
	s_waitcnt lgkmcnt(0)
	v_add_f32_e32 v0, v0, v14
	ds_bpermute_b32 v14, v113, v0
	s_waitcnt lgkmcnt(0)
	v_add_f32_e32 v0, v0, v14
	v_fmamk_f32 v0, v0, 0x3a800000, v218
	v_cmp_gt_f32_e32 vcc, s13, v0
	v_mul_f32_e32 v14, 0x4b800000, v0
	s_nop 0
	v_cndmask_b32_e32 v0, v0, v14, vcc
	v_rsq_f32_e32 v0, v0
	s_nop 0
	v_mul_f32_e32 v14, 0x45800000, v0
	v_cndmask_b32_e32 v0, v0, v14, vcc
	global_load_dwordx4 v[14:17], v[76:77], off
	v_mov_b32_e32 v87, v1
	v_mov_b32_e32 v89, v1
	v_mov_b32_e32 v91, v1
	global_load_dwordx4 v[168:171], v[76:77], off offset:1024
	v_lshl_add_u64 v[172:173], v[18:19], 0, v[86:87]
	global_load_dwordx4 v[172:175], v[172:173], off
	global_load_dwordx4 v[176:179], v[26:27], off offset:1024
	global_load_dwordx4 v[180:183], v[76:77], off offset:2048
	v_lshl_add_u64 v[184:185], v[18:19], 0, v[88:89]
	global_load_dwordx4 v[184:187], v[184:185], off
	global_load_dwordx4 v[188:191], v[26:27], off offset:2048
	global_load_dwordx4 v[192:195], v[76:77], off offset:3072
	v_lshl_add_u64 v[196:197], v[18:19], 0, v[90:91]
	global_load_dwordx4 v[196:199], v[196:197], off
	global_load_dwordx4 v[200:203], v[26:27], off offset:3072
	v_pk_mul_f32 v[20:21], v[24:25], v[0:1] op_sel_hi:[1,0]
	v_pk_mul_f32 v[22:23], v[22:23], v[0:1] op_sel_hi:[1,0]
	v_pk_mul_f32 v[12:13], v[12:13], v[0:1] op_sel_hi:[1,0]
	v_pk_mul_f32 v[10:11], v[10:11], v[0:1] op_sel_hi:[1,0]
	v_pk_mul_f32 v[8:9], v[8:9], v[0:1] op_sel_hi:[1,0]
	v_pk_mul_f32 v[6:7], v[6:7], v[0:1] op_sel_hi:[1,0]
	v_pk_mul_f32 v[4:5], v[4:5], v[0:1] op_sel_hi:[1,0]
	v_pk_mul_f32 v[2:3], v[2:3], v[0:1] op_sel_hi:[1,0]
	s_waitcnt vmcnt(9)
	v_pk_mul_f32 v[14:15], v[14:15], v[22:23]
	v_pk_mul_f32 v[16:17], v[16:17], v[20:21]
	v_pk_add_f32 v[20:21], v[30:31], 1.0 op_sel_hi:[1,0]
	v_pk_add_f32 v[22:23], v[28:29], 1.0 op_sel_hi:[1,0]
	v_pk_fma_f32 v[16:17], v[20:21], v[16:17], v[34:35]
	v_pk_fma_f32 v[14:15], v[22:23], v[14:15], v[32:33]
	v_lshl_add_u64 v[20:21], v[80:81], 0, v[36:37]
	v_cvt_pk_bf16_f32 v14, v14, v15
	v_cvt_pk_bf16_f32 v15, v16, v17
	global_store_dwordx2 v[20:21], v[14:15], off
	v_lshl_add_u64 v[22:23], v[18:19], 0, v[86:87]
	s_waitcnt vmcnt(7)
	v_pk_mul_f32 v[10:11], v[168:169], v[10:11]
	v_pk_mul_f32 v[12:13], v[170:171], v[12:13]
	v_pk_add_f32 v[14:15], v[174:175], 1.0 op_sel_hi:[1, 0]
	v_pk_add_f32 v[16:17], v[172:173], 1.0 op_sel_hi:[1, 0]
	v_pk_fma_f32 v[12:13], v[14:15], v[12:13], v[178:179]
	v_pk_fma_f32 v[10:11], v[16:17], v[10:11], v[176:177]
	v_lshl_add_u64 v[14:15], v[18:19], 0, v[88:89]
	v_cvt_pk_bf16_f32 v10, v10, v11
	v_cvt_pk_bf16_f32 v11, v12, v13
	global_store_dwordx2 v[20:21], v[10:11], off offset:512
	s_waitcnt vmcnt(5)
	v_pk_mul_f32 v[6:7], v[180:181], v[6:7]
	v_pk_mul_f32 v[8:9], v[182:183], v[8:9]
	v_pk_add_f32 v[10:11], v[186:187], 1.0 op_sel_hi:[1, 0]
	v_pk_add_f32 v[12:13], v[184:185], 1.0 op_sel_hi:[1, 0]
	v_pk_fma_f32 v[8:9], v[10:11], v[8:9], v[190:191]
	v_pk_fma_f32 v[6:7], v[12:13], v[6:7], v[188:189]
	v_lshl_add_u64 v[10:11], v[18:19], 0, v[90:91]
	v_cvt_pk_bf16_f32 v6, v6, v7
	v_cvt_pk_bf16_f32 v7, v8, v9
	global_store_dwordx2 v[20:21], v[6:7], off offset:1024
	s_waitcnt vmcnt(3)
	v_pk_mul_f32 v[2:3], v[2:3], v[192:193]
	v_pk_mul_f32 v[4:5], v[4:5], v[194:195]
	v_pk_add_f32 v[6:7], v[198:199], 1.0 op_sel_hi:[1, 0]
	v_pk_add_f32 v[8:9], v[196:197], 1.0 op_sel_hi:[1, 0]
	v_pk_fma_f32 v[4:5], v[4:5], v[6:7], v[202:203]
	v_pk_fma_f32 v[2:3], v[2:3], v[8:9], v[200:201]
	s_nop 0
	v_cvt_pk_bf16_f32 v2, v2, v3
	v_cvt_pk_bf16_f32 v3, v4, v5
	global_store_dwordx2 v[20:21], v[2:3], off offset:1536
	s_branch .LBB0_442
	s_nop 0
	s_nop 0
	s_nop 0
	s_nop 0
	s_nop 0
	s_nop 0
	s_nop 0
	s_nop 0
	s_nop 0
	s_nop 0
	s_nop 0
	s_nop 0
	s_nop 0
	s_nop 0
	s_nop 0
	s_nop 0
	s_nop 0
	s_nop 0
	s_nop 0
	s_nop 0
	s_nop 0
	s_nop 0
	s_nop 0
	s_nop 0
	s_nop 0
	s_nop 0
	s_nop 0
	s_nop 0
	s_nop 0
	s_nop 0
	s_nop 0
	s_nop 0
	s_nop 0
	s_nop 0
	s_nop 0
	s_nop 0
	s_nop 0
	s_nop 0
	s_nop 0
	s_nop 0
	s_nop 0
	s_nop 0
	s_nop 0
	s_nop 0
	s_nop 0
